# attention tile loop: static s_setprio 1 for waves 0-3 (older half) instead
# baseline (speedup 1.0000x reference)
; #define LAS __attribute__((address_space(3)))
; __device__ __forceinline__ void attn_unit(const bf16_t* Q, const bf16_t* K, const bf16_t* Vt, int ntiles, int nrows, bf16_t* O, float negM, LAS unsigned char* lds, int tid) {
;     const int lane = tid & 63, w = tid >> 6, r32 = lane & 31, hi = lane >> 5;
;     const int row0 = w * 64 + r32, row1 = row0 + 32;
;     bf16x8 qa[4], qb[4];
;     {
;         const bf16_t* qp0 = Q + (size_t)min(row0, nrows - 1) * 64 + hi * 8;
;         const bf16_t* qp1 = Q + (size_t)min(row1, nrows - 1) * 64 + hi * 8;
; #pragma unroll
;         for (int s = 0; s < 4; ++s) { qa[s] = *(const bf16x8*)(qp0 + 16 * s); qb[s] = *(const bf16x8*)(qp1 + 16 * s); }
;     }
;     LAS unsigned char* qlds = lds + 40960 + w * 4096 + lane * 16;
; #pragma unroll
;     for (int s = 0; s < 4; ++s) *(LAS bf16x8*)(qlds + s * 1024) = qb[s];
;     f32x16 oa0, oa1, ob0, ob1;
; #pragma unroll
;     for (int e = 0; e < 16; ++e) { oa0[e] = 0.f; oa1[e] = 0.f; ob0[e] = 0.f; ob1[e] = 0.f; }
;     float lsa = 0.f, lsb = 0.f;
;     const int srow = tid >> 3, sch = tid & 7;
;     const bf16_t* kg = K + srow * 64 + sch * 8;
;     const bf16_t* vg = Vt + (size_t)srow * TKV + sch * 8;
;     const int soff = srow * 144 + sch * 16;
;     u32x4 kr = *(const u32x4*)kg, vr = *(const u32x4*)vg;
;     *(LAS u32x4*)(lds + soff) = kr; *(LAS u32x4*)(lds + 9216 + soff) = vr;
;     __syncthreads();
;     const int foff = r32 * 144 + hi * 16;
;     ...
;     asm volatile("" : "+s"(ntiles));
.Lattn_noremap:
	s_add_i32 s4, s7, 0xfffffe00
	s_cmpk_lt_i32 s7, 0x200
	s_cselect_b64 s[0:1], -1, 0
	s_and_b64 s[0:1], s[0:1], exec
	s_cselect_b32 s4, s7, s4
	s_cselect_b32 s8, s14, 0x100
	s_cselect_b32 s13, 0x44, 4
	s_lshl_b32 s0, s4, 9
	s_and_b32 s9, s0, 0xe00
	s_or_b32 s5, s9, 0x100
	s_cmpk_lt_i32 s7, 0x200
	s_cselect_b64 s[0:1], -1, 0
	s_and_b64 s[0:1], s[0:1], exec
	s_cselect_b32 s28, s5, 0
	s_ashr_i32 s10, s4, 3
	s_cmpk_lt_i32 s7, 0x200
	s_cselect_b64 s[0:1], -1, 0
	s_and_b64 s[0:1], s[0:1], exec
	s_cselect_b32 s29, s10, s7
	s_ashr_i32 s12, s7, 6
	s_cmpk_lt_i32 s7, 0x200
	s_cselect_b64 s[0:1], -1, 0
	s_and_b64 s[4:5], s[0:1], exec
	s_cselect_b32 s5, s12, s10
	s_and_b32 s11, s29, 7
	s_bfe_u32 s4, s29, 0x10002
	s_lshl_b32 s29, s5, 3
	s_or_b32 s29, s29, s11
	s_mul_hi_i32 s30, s29, 0x1100
	s_mulk_i32 s29, 0x1100
	s_add_u32 s28, s29, s28
	s_addc_u32 s29, s30, 0
	s_lshl_b64 s[28:29], s[28:29], 7
	s_add_u32 s28, s34, s28
	s_addc_u32 s29, s35, s29
	s_add_i32 s31, s8, -1
	v_min_i32_e32 v16, s31, v170
	v_ashrrev_i32_e32 v17, 31, v16
	v_lshlrev_b64 v[16:17], 7, v[16:17]
	v_lshl_add_u64 v[16:17], s[28:29], 0, v[16:17]
	v_lshl_add_u64 v[28:29], v[16:17], 0, v[186:187]
	v_min_i32_e32 v16, s31, v172
	v_ashrrev_i32_e32 v17, 31, v16
	v_lshlrev_b64 v[16:17], 7, v[16:17]
	v_lshl_add_u64 v[16:17], s[28:29], 0, v[16:17]
	v_lshl_add_u64 v[30:31], v[16:17], 0, v[186:187]
	global_load_dwordx4 v[146:149], v[28:29], off
	global_load_dwordx4 v[150:153], v[28:29], off offset:32
	global_load_dwordx4 v[154:157], v[28:29], off offset:64
	global_load_dwordx4 v[158:161], v[28:29], off offset:96
	global_load_dwordx4 v[96:99], v[30:31], off
	global_load_dwordx4 v[100:103], v[30:31], off offset:32
	global_load_dwordx4 v[104:107], v[30:31], off offset:64
	global_load_dwordx4 v[108:111], v[30:31], off offset:96
	s_lshl_b32 s5, s5, 1
	s_or_b32 s30, s4, s5
	v_mad_i64_i32 v[112:113], s[28:29], s30, v233, v[174:175]
	v_mad_i64_i32 v[114:115], s[28:29], s30, v233, v[176:177]
	global_load_dwordx4 v[162:165], v[112:113], off
	global_load_dwordx4 v[166:169], v[114:115], off
	v_mad_i64_i32 v[196:197], s[4:5], s30, v233, v[184:185]
	v_mad_i64_i32 v[198:199], s[4:5], s30, v233, v[192:193]
	v_mov_b32_e32 v173, v181
	s_movk_i32 s28, 0x4800
	v_add_u32_e32 v188, s28, v181
	s_mov_b32 s29, 0
	v_mov_b32_e32 v194, 0
	v_mov_b32_e32 v195, 0
	v_mov_b32_e32 v226, 0
	v_mov_b32_e32 v227, 0
	v_mov_b32_e32 v246, 0
	v_mov_b32_e32 v247, 0
	v_mov_b32_e32 v16, 0
	v_mov_b32_e32 v17, 0
	v_mov_b32_e32 v18, 0
	v_mov_b32_e32 v19, 0
	v_mov_b32_e32 v20, 0
	v_mov_b32_e32 v21, 0
	v_mov_b32_e32 v22, 0
	v_mov_b32_e32 v23, 0
	v_mov_b32_e32 v24, 0
	v_mov_b32_e32 v25, 0
	v_mov_b32_e32 v26, 0
	v_mov_b32_e32 v27, 0
	v_mov_b32_e32 v28, 0
	v_mov_b32_e32 v29, 0
	v_mov_b32_e32 v30, 0
	v_mov_b32_e32 v31, 0
	v_mov_b32_e32 v32, 0
	v_mov_b32_e32 v33, 0
	v_mov_b32_e32 v34, 0
	v_mov_b32_e32 v35, 0
	v_mov_b32_e32 v36, 0
	v_mov_b32_e32 v37, 0
	v_mov_b32_e32 v38, 0
	v_mov_b32_e32 v39, 0
	v_mov_b32_e32 v40, 0
	v_mov_b32_e32 v41, 0
	v_mov_b32_e32 v42, 0
	v_mov_b32_e32 v43, 0
	v_mov_b32_e32 v44, 0
	v_mov_b32_e32 v45, 0
	v_mov_b32_e32 v46, 0
	v_mov_b32_e32 v47, 0
	v_mov_b32_e32 v48, 0
	v_mov_b32_e32 v49, 0
	v_mov_b32_e32 v50, 0
	v_mov_b32_e32 v51, 0
	v_mov_b32_e32 v52, 0
	v_mov_b32_e32 v53, 0
	v_mov_b32_e32 v54, 0
	v_mov_b32_e32 v55, 0
	v_mov_b32_e32 v56, 0
	v_mov_b32_e32 v57, 0
	v_mov_b32_e32 v58, 0
	v_mov_b32_e32 v59, 0
	v_mov_b32_e32 v60, 0
	v_mov_b32_e32 v61, 0
	v_mov_b32_e32 v62, 0
	v_mov_b32_e32 v63, 0
	v_mov_b32_e32 v64, 0
	v_mov_b32_e32 v65, 0
	v_mov_b32_e32 v66, 0
	v_mov_b32_e32 v67, 0
	v_mov_b32_e32 v68, 0
	v_mov_b32_e32 v69, 0
	v_mov_b32_e32 v70, 0
	v_mov_b32_e32 v71, 0
	v_mov_b32_e32 v72, 0
	v_mov_b32_e32 v73, 0
	v_mov_b32_e32 v74, 0
	v_mov_b32_e32 v75, 0
	v_mov_b32_e32 v76, 0
	v_mov_b32_e32 v77, 0
	v_mov_b32_e32 v78, 0
	v_mov_b32_e32 v79, 0
	v_mov_b32_e32 v238, 0
	v_mov_b32_e32 v239, 0
	v_mov_b32_e32 v240, 0
	v_mov_b32_e32 v241, 0
	v_mov_b32_e32 v242, 0
	v_mov_b32_e32 v243, 0
	v_mov_b32_e32 v244, 0
	v_mov_b32_e32 v245, 0
	s_waitcnt vmcnt(0)
	ds_write_b128 v145, v[162:165]
	ds_write_b128 v145, v[166:169] offset:9216
	global_load_dwordx4 v[162:165], v[198:199], off
	global_load_dwordx4 v[166:169], v[196:197], off
	v_lshl_add_u64 v[198:199], v[198:199], 0, s[80:81]
	v_lshl_add_u64 v[196:197], v[196:197], 0, s[44:45]
	s_waitcnt lgkmcnt(0)
	s_barrier
	ds_read_b128 v[80:83], v173
	ds_read_b128 v[84:87], v173 offset:32
	ds_read_b128 v[88:91], v173 offset:64
	ds_read_b128 v[92:95], v173 offset:96
	ds_read_b128 v[200:203], v173 offset:9280
	ds_read_b128 v[204:207], v173 offset:13888
	ds_read_b128 v[208:211], v173 offset:9312
	ds_read_b128 v[212:215], v173 offset:13920
	s_waitcnt lgkmcnt(7)
	v_mfma_f32_32x32x16_bf16 v[112:127], v[80:83], v[146:149], v[0:15]
	s_waitcnt lgkmcnt(6)
	v_mfma_f32_32x32x16_bf16 v[112:127], v[84:87], v[150:153], v[112:127]
	s_waitcnt lgkmcnt(5)
	v_mfma_f32_32x32x16_bf16 v[112:127], v[88:91], v[154:157], v[112:127]
	s_waitcnt lgkmcnt(4)
	v_mfma_f32_32x32x16_bf16 v[112:127], v[92:95], v[158:161], v[112:127]
	s_waitcnt lgkmcnt(0)
	s_nop 7
	s_nop 3
	v_cmp_gt_u32_e32 vcc, 0x100, v144
	s_cbranch_vccz .Lattn_noprio
	s_setprio 1
